# prologue de-serialisation: the four GEMM preambles' second load-batch wait relaxed from vmcnt(6) to vmcnt(10) (first tile needs only the first four loads before its first reads)
# speedup vs baseline: 1.0109x; 1.0027x over previous
.LBB0_368:
	s_and_b32 s16, s8, 3
	s_lshl_b32 s17, s13, 13
	s_lshl_b32 s19, s16, 12
	s_add_u32 s8, s4, 0xa5b8000
	s_mov_b64 s[10:11], 0x80
	s_addc_u32 s9, s5, 0
	s_add_i32 m0, s39, 0x18000
	v_lshl_add_u64 v[8:9], v[8:9], 0, s[10:11]
	s_ashr_i32 s44, s33, 31
	s_waitcnt vmcnt(4)
	s_barrier
	global_load_lds_dwordx4 v[8:9], off
	v_lshl_add_u64 v[6:7], v[6:7], 0, s[10:11]
	s_add_i32 m0, s39, 0x1a000
	s_add_i32 s45, s39, 0x8000
	s_add_i32 s46, s39, 0xa000
	global_load_lds_dwordx4 v[6:7], off
	v_lshl_add_u64 v[4:5], v[4:5], 0, s[10:11]
	s_mov_b32 m0, s45
	s_add_u32 s14, s26, 0x80080
	global_load_lds_dwordx4 v[4:5], off
	v_lshl_add_u64 v[2:3], v[2:3], 0, s[10:11]
	s_mov_b32 m0, s46
	s_addc_u32 s15, s27, 0
	global_load_lds_dwordx4 v[2:3], off
	s_add_i32 m0, s39, 0x1c000
	v_lshl_add_u64 v[2:3], s[14:15], 0, v[130:131]
	global_load_lds_dwordx4 v[2:3], off
	v_lshl_add_u64 v[2:3], s[14:15], 0, v[132:133]
	s_add_i32 m0, s39, 0x1e000
	v_bfe_u32 v4, v10, 4, 2
	global_load_lds_dwordx4 v[2:3], off
	v_and_b32_e32 v3, 15, v10
	v_lshlrev_b32_e32 v2, 4, v4
	v_lshlrev_b32_e32 v6, 2, v10
	v_and_b32_e32 v6, 32, v6
	v_lshl_or_b32 v146, s13, 6, v3
	v_lshl_or_b32 v3, v3, 6, v2
	s_sext_i32_i8 s50, s12
	v_lshlrev_b32_e32 v5, 6, v10
	s_movk_i32 s12, 0x3c0
	v_bitop3_b32 v7, v3, s17, v6 bitop3:0xde
	v_mov_b32_e32 v3, v131
	v_and_or_b32 v5, v5, s12, v2
	v_lshl_add_u64 v[2:3], s[4:5], 0, v[2:3]
	s_mov_b64 s[4:5], 0x62b0000
	v_lshl_add_u64 v[134:135], v[2:3], 0, s[4:5]
	v_lshlrev_b32_e32 v2, 9, v10
	v_and_b32_e32 v2, 0x70000, v2
	v_lshlrev_b32_e32 v3, 12, v13
	v_or3_b32 v2, v11, v2, v3
	v_add_u32_e32 v136, v2, v12
	v_lshlrev_b32_e32 v2, 5, v14
	s_waitcnt vmcnt(10)
	s_cmp_eq_u32 s16, 0
	v_and_b32_e32 v2, 0xf0000, v2
	v_bitop3_b32 v147, s19, v5, v6 bitop3:0xf6
	v_lshlrev_b32_e32 v4, 2, v4
	s_cselect_b64 s[12:13], -1, 0
	v_or3_b32 v2, v11, v2, v3
	s_add_i32 s47, 0, 0x10000
	s_add_i32 s48, 0, 0x14000
	v_and_b32_e32 v144, 4, v4
	v_and_b32_e32 v145, 8, v4
	v_lshlrev_b32_e32 v144, 2, v144
	v_or_b32_e32 v144, v144, v145
	v_lshl_or_b32 v148, s16, 5, v144
	v_mov_b32_e32 v137, v131
	v_add_u32_e32 v138, v2, v12
	v_mov_b32_e32 v139, v131
	v_mov_b64_e32 v[140:141], 0x5ee
	v_mov_b64_e32 v[142:143], 0x5ed
	v_add_u32_e32 v149, s47, v147
	v_add_u32_e32 v150, 0, v7
	v_add_u32_e32 v151, s48, v147
	s_movk_i32 s49, 0x2c00
	s_barrier
	s_cmpk_lt_u32 s34, 0x1000
	s_cbranch_scc0 .Lp2_prio_done
	s_setprio 1

.LBB0_937:
	s_lshl_b32 s14, s14, 5
	s_and_b32 s19, s14, 0x60
	s_mov_b64 s[14:15], 0x80
	s_add_i32 m0, s37, 0x18000
	v_lshl_add_u64 v[2:3], v[2:3], 0, s[14:15]
	s_lshl_b32 s18, s5, 13
	s_waitcnt vmcnt(4)
	s_barrier
	global_load_lds_dwordx4 v[2:3], off
	v_lshl_add_u64 v[2:3], v[4:5], 0, s[14:15]
	s_add_i32 m0, s37, 0x1a000
	s_add_i32 s57, s37, 0x8000
	s_add_i32 s58, s37, 0xa000
	global_load_lds_dwordx4 v[2:3], off
	v_lshl_add_u64 v[2:3], v[8:9], 0, s[14:15]
	s_mov_b32 m0, s57
	s_add_u32 s16, s40, 0x80080
	global_load_lds_dwordx4 v[2:3], off
	v_lshl_add_u64 v[2:3], v[6:7], 0, s[14:15]
	s_mov_b32 m0, s58
	s_addc_u32 s17, s41, 0
	global_load_lds_dwordx4 v[2:3], off
	s_add_i32 m0, s37, 0x1c000
	v_lshl_add_u64 v[2:3], s[16:17], 0, v[146:147]
	global_load_lds_dwordx4 v[2:3], off
	v_lshl_add_u64 v[2:3], s[16:17], 0, v[148:149]
	s_add_i32 m0, s37, 0x1e000
	v_and_b32_e32 v4, 15, v0
	global_load_lds_dwordx4 v[2:3], off
	v_lshlrev_b32_e32 v3, 2, v4
	v_lshl_or_b32 v2, v4, 6, v1
	v_and_b32_e32 v3, 32, v3
	v_bitop3_b32 v2, v2, s18, v3 bitop3:0xde
	v_lshlrev_b32_e32 v3, 9, v162
	v_lshl_or_b32 v163, s5, 6, v4
	v_and_b32_e32 v3, 0x70000, v3
	v_lshlrev_b32_e32 v4, 12, v12
	v_or3_b32 v3, v10, v3, v4
	v_add_u32_e32 v150, v3, v11
	v_lshlrev_b32_e32 v3, 5, v13
	s_waitcnt vmcnt(10)
	v_and_b32_e32 v3, 0x70000, v3
	v_lshl_or_b32 v164, s19, 7, v161
	v_mov_b32_e32 v151, 0
	v_or3_b32 v3, v10, v3, v4
	s_add_i32 s59, 0, 0x10000
	s_add_i32 s60, 0, 0x14000
	s_sext_i32_i8 s62, s4
	v_or_b32_e32 v165, s19, v254
	v_add_u32_e32 v152, v3, v11
	v_mov_b32_e32 v153, v151
	v_mov_b64_e32 v[154:155], 0x200
	v_mov_b64_e32 v[156:157], 0x1ff
	v_add_u32_e32 v167, s59, v164
	v_add_u32_e32 v170, 0, v2
	v_add_u32_e32 v171, s60, v164
	s_mov_b64 s[16:17], 0x6104000
	s_mov_b32 s61, 0x6104000
	s_mov_b64 s[18:19], 0x100000
	s_mov_b64 s[20:21], 0x120000
	s_mov_b64 s[22:23], 0x140000
	s_mov_b64 s[24:25], 0x160000
	s_barrier
	s_cmpk_lt_u32 s47, 0x1000
	s_cbranch_scc0 .Lp6_prio_done
	s_setprio 1

.LBB0_1093:
	s_lshl_b32 s4, s4, 5
	s_and_b32 s10, s4, 0x60
	s_lshl_b32 s6, s55, 13
	s_lshl_b32 s7, s10, 7
	s_add_u32 s22, s18, 0xa5b8000
	s_addc_u32 s23, s19, 0
	s_add_u32 s24, s18, 0x15b38000
	s_addc_u32 s25, s19, 0
	s_add_u32 s26, s18, 0x17138000
	s_addc_u32 s27, s19, 0
	s_add_u32 s28, s18, 0x18738000
	s_addc_u32 s29, s19, 0
	s_ashr_i32 s63, s33, 31
	s_add_u32 s30, s12, 0xb000
	s_addc_u32 s31, s13, 0
	s_add_u32 s34, s12, 0x16000
	s_mov_b64 s[36:37], 0x80
	s_addc_u32 s35, s13, 0
	s_add_i32 m0, s21, 0x18000
	v_lshl_add_u64 v[8:9], v[8:9], 0, s[36:37]
	s_waitcnt vmcnt(4)
	s_barrier
	global_load_lds_dwordx4 v[8:9], off
	v_lshl_add_u64 v[6:7], v[6:7], 0, s[36:37]
	s_add_i32 m0, s21, 0x1a000
	s_add_i32 s64, s21, 0x8000
	s_add_i32 s65, s21, 0xa000
	global_load_lds_dwordx4 v[6:7], off
	v_lshl_add_u64 v[4:5], v[4:5], 0, s[36:37]
	s_mov_b32 m0, s64
	s_add_u32 s4, s50, 0x80080
	global_load_lds_dwordx4 v[4:5], off
	v_lshl_add_u64 v[2:3], v[2:3], 0, s[36:37]
	s_mov_b32 m0, s65
	s_addc_u32 s5, s51, 0
	global_load_lds_dwordx4 v[2:3], off
	s_add_i32 m0, s21, 0x1c000
	v_lshl_add_u64 v[2:3], s[4:5], 0, v[162:163]
	global_load_lds_dwordx4 v[2:3], off
	v_lshl_add_u64 v[2:3], s[4:5], 0, v[164:165]
	s_add_i32 m0, s21, 0x1e000
	v_lshlrev_b32_e32 v4, 6, v10
	global_load_lds_dwordx4 v[2:3], off
	v_bfe_u32 v2, v10, 4, 2
	v_lshlrev_b32_e32 v3, 4, v2
	s_movk_i32 s4, 0x3c0
	v_lshlrev_b32_e32 v5, 2, v10
	v_and_or_b32 v4, v4, s4, v3
	v_and_b32_e32 v5, 32, v5
	v_lshl_or_b32 v239, v2, 2, s10
	v_lshlrev_b32_e32 v2, 9, v10
	v_bitop3_b32 v236, s7, v4, v5 bitop3:0xf6
	v_and_b32_e32 v2, 0x70000, v2
	v_lshlrev_b32_e32 v4, 12, v13
	v_or3_b32 v2, v11, v2, v4
	v_and_b32_e32 v1, 15, v10
	v_add_u32_e32 v166, v2, v12
	v_lshlrev_b32_e32 v2, 5, v14
	v_lshl_or_b32 v3, v1, 6, v3
	s_waitcnt vmcnt(10)
	v_and_b32_e32 v2, 0xf0000, v2
	v_lshl_or_b32 v6, s55, 6, v1
	v_bitop3_b32 v3, v3, s6, v5 bitop3:0xde
	v_or3_b32 v2, v11, v2, v4
	s_add_i32 s68, 0, 0x10000
	s_add_i32 s69, 0, 0x14000
	v_cmp_gt_u32_e64 s[4:5], 2, v1
	v_cmp_lt_u32_e64 s[6:7], 13, v1
	v_add_u32_e32 v237, -14, v1
	v_cmp_lt_u32_e64 s[8:9], 1, v1
	v_add_u32_e32 v238, 0xffffc000, v6
	s_ashr_i32 s66, s3, 31
	v_mov_b32_e32 v167, v163
	v_add_u32_e32 v170, v2, v12
	v_mov_b32_e32 v171, v163
	v_mov_b64_e32 v[172:173], 0xbb0
	v_mov_b64_e32 v[174:175], 0xbaf
	s_movk_i32 s67, 0x16c
	s_mov_b32 s87, 28
	v_and_b32_e32 v245, 31, v0
	v_lshlrev_b32_e32 v245, 4, v245
	v_bfe_u32 v250, v0, 5, 1
	v_mul_u32_u24_e32 v250, 0x5800, v250
	v_add_u32_e32 v245, v245, v250
	v_lshlrev_b32_e32 v250, 2, v239
	s_mov_b32 s86, 0x20000
	s_cmpk_lt_u32 s56, 0x1000
	s_cbranch_scc0 .Lp8_prio_done
	s_setprio 1

.LBB0_1285:
	s_mov_b64 s[18:19], 0x80
	s_lshl_b32 s6, s6, 5
	s_add_i32 m0, s43, 0x18000
	v_lshl_add_u64 v[8:9], v[8:9], 0, s[18:19]
	s_lshl_b32 s8, s4, 13
	s_and_b32 s9, s6, 0x60
	s_waitcnt vmcnt(4)
	s_barrier
	global_load_lds_dwordx4 v[8:9], off
	v_lshl_add_u64 v[6:7], v[6:7], 0, s[18:19]
	s_add_i32 m0, s43, 0x1a000
	s_add_i32 s48, s43, 0x8000
	s_add_i32 s49, s43, 0xa000
	global_load_lds_dwordx4 v[6:7], off
	v_lshl_add_u64 v[4:5], v[4:5], 0, s[18:19]
	s_mov_b32 m0, s48
	s_add_u32 s6, s30, 0x160080
	global_load_lds_dwordx4 v[4:5], off
	v_lshl_add_u64 v[2:3], v[2:3], 0, s[18:19]
	s_mov_b32 m0, s49
	s_addc_u32 s7, s31, 0
	global_load_lds_dwordx4 v[2:3], off
	s_add_i32 m0, s43, 0x1c000
	v_lshl_add_u64 v[2:3], s[6:7], 0, v[146:147]
	global_load_lds_dwordx4 v[2:3], off
	v_lshl_add_u64 v[2:3], s[6:7], 0, v[148:149]
	s_add_i32 m0, s43, 0x1e000
	v_and_b32_e32 v4, 15, v0
	global_load_lds_dwordx4 v[2:3], off
	v_lshlrev_b32_e32 v3, 2, v4
	v_lshl_or_b32 v2, v4, 6, v167
	v_and_b32_e32 v3, 32, v3
	s_waitcnt vmcnt(10)
	v_bitop3_b32 v2, v2, s8, v3 bitop3:0xde
	v_lshl_or_b32 v173, s9, 7, v170
	v_bfe_u32 v3, v0, 4, 2
	s_add_i32 s51, 0, 0x10000
	s_add_i32 s52, 0, 0x14000
	s_sext_i32_i8 s57, s5
	v_lshl_or_b32 v172, s4, 6, v4
	s_ashr_i32 s50, s33, 31
	v_lshl_or_b32 v174, v3, 2, s9
	v_add3_u32 v150, v165, v1, v164
	v_mov_b32_e32 v151, v147
	v_add3_u32 v152, v166, v1, v164
	v_mov_b32_e32 v153, v147
	v_mov_b64_e32 v[154:155], 0x200
	v_mov_b64_e32 v[156:157], 0x1ff
	v_add_u32_e32 v175, s51, v173
	v_add_u32_e32 v176, 0, v2
	v_add_u32_e32 v177, s52, v173
	s_mov_b64 s[20:21], 0x610a000
	s_mov_b32 s53, 0x610a000
	s_mov_b64 s[22:23], 0x100000
	s_mov_b64 s[24:25], 0x120000
	s_mov_b64 s[26:27], 0x140000
	s_barrier
	s_cmpk_lt_u32 s40, 0x1000
	s_cbranch_scc0 .Lp10_prio_done
	s_setprio 1
